# sync polls: sleep before the first poll (non-last leaders 127, XCD-last 24, group sync 40), then as before
# speedup vs baseline: 1.0354x; 1.0063x over previous
.LBB0_146:
	s_or_b64 exec, exec, s[4:5]
	s_cmp_lt_u32 s61, 2
	s_cbranch_scc1 .LBB0_200
	s_waitcnt vmcnt(0) lgkmcnt(0)
	s_barrier
	v_readfirstlane_b32 s2, v162
	s_lshl_b32 s3, s33, 8
	s_add_u32 s6, s84, s3
	s_addc_u32 s7, s85, 0
	s_cmp_lg_u32 s2, 0
	s_cbranch_scc1 .Lgb1_wait
	s_mov_b64 s[8:9], exec
	s_mov_b64 exec, 1
	v_mov_b32_e32 v0, 0x12000
	ds_read_b64 v[2:3], v0
	v_mov_b32_e32 v0, 0x1400
	v_mov_b32_e32 v1, 1
	global_atomic_add v4, v0, v1, s[6:7] sc0
	s_mov_b32 s13, 0
	s_add_u32 s14, s84, 0x2480
	s_addc_u32 s15, s85, 0
	s_waitcnt lgkmcnt(0)
	v_readfirstlane_b32 s10, v2
	v_readfirstlane_b32 s11, v3
	v_mov_b32_e32 v0, 0
	s_nop 3
	s_mul_i32 s10, s10, 2
	s_mul_i32 s11, s11, 1
	s_waitcnt vmcnt(0)
	v_readfirstlane_b32 s12, v4
	s_nop 3
	s_add_u32 s12, s12, 1
	s_cmp_lg_u32 s12, s10
	s_cbranch_scc1 .Lgb1_poll
	buffer_wbl2 sc1
	s_waitcnt vmcnt(0)
	global_atomic_add v0, v1, s[14:15] offset:0
	global_atomic_add v0, v1, s[14:15] offset:256
	global_atomic_add v0, v1, s[14:15] offset:512
	global_atomic_add v0, v1, s[14:15] offset:768
	global_atomic_add v0, v1, s[14:15] offset:1024
	global_atomic_add v0, v1, s[14:15] offset:1280
	global_atomic_add v0, v1, s[14:15] offset:1536
	global_atomic_add v0, v1, s[14:15] offset:1792
	global_atomic_add v0, v1, s[14:15] offset:2048
	global_atomic_add v0, v1, s[14:15] offset:2304
	global_atomic_add v0, v1, s[14:15] offset:2560
	global_atomic_add v0, v1, s[14:15] offset:2816
	global_atomic_add v0, v1, s[14:15] offset:3072
	global_atomic_add v0, v1, s[14:15] offset:3328
	global_atomic_add v0, v1, s[14:15] offset:3584
	global_atomic_add v0, v1, s[14:15] offset:3840
	v_mov_b32_e32 v0, 0x2480
.Lgb1_tloop:
	s_sleep 24
	global_load_dword v4, v0, s[6:7] sc1
	s_add_u32 s13, s13, 1
	s_waitcnt vmcnt(0)
	v_readfirstlane_b32 s12, v4
	s_nop 3
	s_cmp_gt_u32 s13, 0x80000
	s_cbranch_scc1 .Lgb1_done
	s_cmp_ge_u32 s12, s11
	s_cbranch_scc1 .Lgb1_done
	s_branch .Lgb1_tloop
.Lgb1_poll:
	v_mov_b32_e32 v0, 0x2480
	s_sleep 127
	s_branch .Lgb1_l2
.Lgb1_loop:
	s_sleep 127
.Lgb1_l2:
	global_load_dword v4, v0, s[6:7] sc1
	s_add_u32 s13, s13, 1
	s_waitcnt vmcnt(0)
	v_readfirstlane_b32 s12, v4
	s_nop 3
	s_cmp_gt_u32 s13, 0x80000
	s_cbranch_scc1 .Lgb1_done
	s_cmp_ge_u32 s12, s11
	s_cbranch_scc1 .Lgb1_done
	s_branch .Lgb1_loop

.LBB0_418:
	s_cmp_lt_i32 s61, 3
	s_cbranch_scc1 .LBB0_472
	s_waitcnt vmcnt(0) lgkmcnt(0)
	s_barrier
	v_readfirstlane_b32 s2, v162
	s_lshl_b32 s3, s33, 8
	s_add_u32 s6, s84, s3
	s_addc_u32 s7, s85, 0
	s_cmp_lg_u32 s2, 0
	s_cbranch_scc1 .Lgb2_wait
	s_mov_b64 s[8:9], exec
	s_mov_b64 exec, 1
	v_mov_b32_e32 v0, 0x12000
	ds_read_b64 v[2:3], v0
	v_mov_b32_e32 v0, 0x1400
	v_mov_b32_e32 v1, 1
	global_atomic_add v4, v0, v1, s[6:7] sc0
	s_mov_b32 s13, 0
	s_add_u32 s14, s84, 0x2480
	s_addc_u32 s15, s85, 0
	s_waitcnt lgkmcnt(0)
	v_readfirstlane_b32 s10, v2
	v_readfirstlane_b32 s11, v3
	v_mov_b32_e32 v0, 0
	s_nop 3
	s_mul_i32 s10, s10, 3
	s_mul_i32 s11, s11, 2
	s_waitcnt vmcnt(0)
	v_readfirstlane_b32 s12, v4
	s_nop 3
	s_add_u32 s12, s12, 1
	s_cmp_lg_u32 s12, s10
	s_cbranch_scc1 .Lgb2_poll
	buffer_wbl2 sc1
	s_waitcnt vmcnt(0)
	global_atomic_add v0, v1, s[14:15] offset:0
	global_atomic_add v0, v1, s[14:15] offset:256
	global_atomic_add v0, v1, s[14:15] offset:512
	global_atomic_add v0, v1, s[14:15] offset:768
	global_atomic_add v0, v1, s[14:15] offset:1024
	global_atomic_add v0, v1, s[14:15] offset:1280
	global_atomic_add v0, v1, s[14:15] offset:1536
	global_atomic_add v0, v1, s[14:15] offset:1792
	global_atomic_add v0, v1, s[14:15] offset:2048
	global_atomic_add v0, v1, s[14:15] offset:2304
	global_atomic_add v0, v1, s[14:15] offset:2560
	global_atomic_add v0, v1, s[14:15] offset:2816
	global_atomic_add v0, v1, s[14:15] offset:3072
	global_atomic_add v0, v1, s[14:15] offset:3328
	global_atomic_add v0, v1, s[14:15] offset:3584
	global_atomic_add v0, v1, s[14:15] offset:3840
	v_mov_b32_e32 v0, 0x2480

.LBB0_491:
	s_or_b64 exec, exec, s[4:5]
	s_cmp_lt_i32 s61, 4
	s_cbranch_scc1 .LBB0_545
	s_waitcnt vmcnt(0) lgkmcnt(0)
	s_barrier
	v_readfirstlane_b32 s2, v162
	s_lshl_b32 s3, s33, 8
	s_add_u32 s6, s84, s3
	s_addc_u32 s7, s85, 0
	s_cmp_lg_u32 s2, 0
	s_cbranch_scc1 .Lgb3_wait
	s_mov_b64 s[8:9], exec
	s_mov_b64 exec, 1
	v_mov_b32_e32 v0, 0x12000
	ds_read_b64 v[2:3], v0
	v_mov_b32_e32 v0, 0x1400
	v_mov_b32_e32 v1, 1
	global_atomic_add v4, v0, v1, s[6:7] sc0
	s_mov_b32 s13, 0
	s_add_u32 s14, s84, 0x2480
	s_addc_u32 s15, s85, 0
	s_waitcnt lgkmcnt(0)
	v_readfirstlane_b32 s10, v2
	v_readfirstlane_b32 s11, v3
	v_mov_b32_e32 v0, 0
	s_nop 3
	s_mul_i32 s10, s10, 4
	s_mul_i32 s11, s11, 3
	s_waitcnt vmcnt(0)
	v_readfirstlane_b32 s12, v4
	s_nop 3
	s_add_u32 s12, s12, 1
	s_cmp_lg_u32 s12, s10
	s_cbranch_scc1 .Lgb3_poll
	buffer_wbl2 sc1
	s_waitcnt vmcnt(0)
	global_atomic_add v0, v1, s[14:15] offset:0
	global_atomic_add v0, v1, s[14:15] offset:256
	global_atomic_add v0, v1, s[14:15] offset:512
	global_atomic_add v0, v1, s[14:15] offset:768
	global_atomic_add v0, v1, s[14:15] offset:1024
	global_atomic_add v0, v1, s[14:15] offset:1280
	global_atomic_add v0, v1, s[14:15] offset:1536
	global_atomic_add v0, v1, s[14:15] offset:1792
	global_atomic_add v0, v1, s[14:15] offset:2048
	global_atomic_add v0, v1, s[14:15] offset:2304
	global_atomic_add v0, v1, s[14:15] offset:2560
	global_atomic_add v0, v1, s[14:15] offset:2816
	global_atomic_add v0, v1, s[14:15] offset:3072
	global_atomic_add v0, v1, s[14:15] offset:3328
	global_atomic_add v0, v1, s[14:15] offset:3584
	global_atomic_add v0, v1, s[14:15] offset:3840
	v_mov_b32_e32 v0, 0x2480

.LBB0_721:
	s_cmp_lt_i32 s61, 5
	s_cbranch_scc1 .LBB0_775
	s_waitcnt vmcnt(0) lgkmcnt(0)
	s_barrier
	v_readfirstlane_b32 s2, v162
	s_lshl_b32 s3, s33, 8
	s_add_u32 s6, s84, s3
	s_addc_u32 s7, s85, 0
	s_cmp_lg_u32 s2, 0
	s_cbranch_scc1 .Lgb4_wait
	s_mov_b64 s[8:9], exec
	s_mov_b64 exec, 1
	v_mov_b32_e32 v0, 0x12000
	ds_read_b64 v[2:3], v0
	v_mov_b32_e32 v0, 0x1400
	v_mov_b32_e32 v1, 1
	global_atomic_add v4, v0, v1, s[6:7] sc0
	s_mov_b32 s13, 0
	s_add_u32 s14, s84, 0x2480
	s_addc_u32 s15, s85, 0
	s_waitcnt lgkmcnt(0)
	v_readfirstlane_b32 s10, v2
	v_readfirstlane_b32 s11, v3
	v_mov_b32_e32 v0, 0
	s_nop 3
	s_mul_i32 s10, s10, 5
	s_mul_i32 s11, s11, 4
	s_waitcnt vmcnt(0)
	v_readfirstlane_b32 s12, v4
	s_nop 3
	s_add_u32 s12, s12, 1
	s_cmp_lg_u32 s12, s10
	s_cbranch_scc1 .Lgb4_poll
	buffer_wbl2 sc1
	s_waitcnt vmcnt(0)
	global_atomic_add v0, v1, s[14:15] offset:0
	global_atomic_add v0, v1, s[14:15] offset:256
	global_atomic_add v0, v1, s[14:15] offset:512
	global_atomic_add v0, v1, s[14:15] offset:768
	global_atomic_add v0, v1, s[14:15] offset:1024
	global_atomic_add v0, v1, s[14:15] offset:1280
	global_atomic_add v0, v1, s[14:15] offset:1536
	global_atomic_add v0, v1, s[14:15] offset:1792
	global_atomic_add v0, v1, s[14:15] offset:2048
	global_atomic_add v0, v1, s[14:15] offset:2304
	global_atomic_add v0, v1, s[14:15] offset:2560
	global_atomic_add v0, v1, s[14:15] offset:2816
	global_atomic_add v0, v1, s[14:15] offset:3072
	global_atomic_add v0, v1, s[14:15] offset:3328
	global_atomic_add v0, v1, s[14:15] offset:3584
	global_atomic_add v0, v1, s[14:15] offset:3840
	v_mov_b32_e32 v0, 0x2480

.LBB0_779:
	s_or_b64 exec, exec, s[8:9]
	s_cmp_lt_u32 s61, 6
	s_cbranch_scc1 .LBB0_833
	s_waitcnt vmcnt(0) lgkmcnt(0)
	s_barrier
	v_readfirstlane_b32 s2, v162
	s_lshl_b32 s3, s33, 8
	s_add_u32 s6, s84, s3
	s_addc_u32 s7, s85, 0
	s_cmp_lg_u32 s2, 0
	s_cbranch_scc1 .Lgb5_wait
	s_mov_b64 s[8:9], exec
	s_mov_b64 exec, 1
	v_mov_b32_e32 v0, 0x12000
	ds_read_b64 v[2:3], v0
	v_mov_b32_e32 v0, 0x1400
	v_mov_b32_e32 v1, 1
	global_atomic_add v4, v0, v1, s[6:7] sc0
	s_mov_b32 s13, 0
	s_add_u32 s14, s84, 0x2480
	s_addc_u32 s15, s85, 0
	s_waitcnt lgkmcnt(0)
	v_readfirstlane_b32 s10, v2
	v_readfirstlane_b32 s11, v3
	v_mov_b32_e32 v0, 0
	s_nop 3
	s_mul_i32 s10, s10, 6
	s_mul_i32 s11, s11, 5
	s_waitcnt vmcnt(0)
	v_readfirstlane_b32 s12, v4
	s_nop 3
	s_add_u32 s12, s12, 1
	s_cmp_lg_u32 s12, s10
	s_cbranch_scc1 .Lgb5_poll
	buffer_wbl2 sc1
	s_waitcnt vmcnt(0)
	global_atomic_add v0, v1, s[14:15] offset:0
	global_atomic_add v0, v1, s[14:15] offset:256
	global_atomic_add v0, v1, s[14:15] offset:512
	global_atomic_add v0, v1, s[14:15] offset:768
	global_atomic_add v0, v1, s[14:15] offset:1024
	global_atomic_add v0, v1, s[14:15] offset:1280
	global_atomic_add v0, v1, s[14:15] offset:1536
	global_atomic_add v0, v1, s[14:15] offset:1792
	global_atomic_add v0, v1, s[14:15] offset:2048
	global_atomic_add v0, v1, s[14:15] offset:2304
	global_atomic_add v0, v1, s[14:15] offset:2560
	global_atomic_add v0, v1, s[14:15] offset:2816
	global_atomic_add v0, v1, s[14:15] offset:3072
	global_atomic_add v0, v1, s[14:15] offset:3328
	global_atomic_add v0, v1, s[14:15] offset:3584
	global_atomic_add v0, v1, s[14:15] offset:3840
	v_mov_b32_e32 v0, 0x2480

.Lr6_end:
.LBB0_839:
	s_cmp_lt_i32 s61, 7
	s_cbranch_scc1 .LBB0_893
	s_waitcnt vmcnt(0)
	s_barrier
	v_readfirstlane_b32 s2, v162
	s_and_b32 s3, s58, 7
	s_lshl_b32 s3, s3, 8
	s_bfe_u32 s6, s58, 0x30003
	s_lshl_b32 s6, s6, 2
	s_add_u32 s3, s3, s6
	s_add_u32 s3, s3, 0x3800
	s_add_u32 s6, s84, s3
	s_addc_u32 s7, s85, 0
	s_cmp_lg_u32 s2, 0
	s_cbranch_scc1 .Lgs6_wait
	s_mov_b64 s[8:9], exec
	s_mov_b64 exec, 1
	v_mov_b32_e32 v0, 0
	v_mov_b32_e32 v1, 1
	s_mov_b32 s10, 0
	global_atomic_add v0, v1, s[6:7]
	s_sleep 40

.LBB0_897:
	s_or_b64 exec, exec, s[10:11]
	s_cmp_lt_u32 s61, 8
	s_cbranch_scc1 .LBB0_951
	s_waitcnt vmcnt(0) lgkmcnt(0)
	s_barrier
	v_readfirstlane_b32 s2, v162
	s_lshl_b32 s3, s33, 8
	s_add_u32 s6, s84, s3
	s_addc_u32 s7, s85, 0
	s_cmp_lg_u32 s2, 0
	s_cbranch_scc1 .Lgb7_wait
	s_mov_b64 s[8:9], exec
	s_mov_b64 exec, 1
	v_mov_b32_e32 v0, 0x12000
	ds_read_b64 v[2:3], v0
	v_mov_b32_e32 v0, 0x1400
	v_mov_b32_e32 v1, 1
	global_atomic_add v4, v0, v1, s[6:7] sc0
	s_mov_b32 s13, 0
	s_add_u32 s14, s84, 0x2480
	s_addc_u32 s15, s85, 0
	s_waitcnt lgkmcnt(0)
	v_readfirstlane_b32 s10, v2
	v_readfirstlane_b32 s11, v3
	v_mov_b32_e32 v0, 0
	s_nop 3
	s_mul_i32 s10, s10, 7
	s_mul_i32 s11, s11, 6
	s_waitcnt vmcnt(0)
	v_readfirstlane_b32 s12, v4
	s_nop 3
	s_add_u32 s12, s12, 1
	s_cmp_lg_u32 s12, s10
	s_cbranch_scc1 .Lgb7_poll
	buffer_wbl2 sc1
	s_waitcnt vmcnt(0)
	global_atomic_add v0, v1, s[14:15] offset:0
	global_atomic_add v0, v1, s[14:15] offset:256
	global_atomic_add v0, v1, s[14:15] offset:512
	global_atomic_add v0, v1, s[14:15] offset:768
	global_atomic_add v0, v1, s[14:15] offset:1024
	global_atomic_add v0, v1, s[14:15] offset:1280
	global_atomic_add v0, v1, s[14:15] offset:1536
	global_atomic_add v0, v1, s[14:15] offset:1792
	global_atomic_add v0, v1, s[14:15] offset:2048
	global_atomic_add v0, v1, s[14:15] offset:2304
	global_atomic_add v0, v1, s[14:15] offset:2560
	global_atomic_add v0, v1, s[14:15] offset:2816
	global_atomic_add v0, v1, s[14:15] offset:3072
	global_atomic_add v0, v1, s[14:15] offset:3328
	global_atomic_add v0, v1, s[14:15] offset:3584
	global_atomic_add v0, v1, s[14:15] offset:3840
	v_mov_b32_e32 v0, 0x2480

.Lf8_end:
.LBB0_961:
	s_cmp_lt_i32 s61, 9
	s_cbranch_scc1 .LBB0_1015
	s_waitcnt vmcnt(0) lgkmcnt(0)
	s_barrier
	v_readfirstlane_b32 s2, v162
	s_lshl_b32 s3, s33, 8
	s_add_u32 s6, s84, s3
	s_addc_u32 s7, s85, 0
	s_cmp_lg_u32 s2, 0
	s_cbranch_scc1 .Lgb8_wait
	s_mov_b64 s[8:9], exec
	s_mov_b64 exec, 1
	v_mov_b32_e32 v0, 0x12000
	ds_read_b64 v[2:3], v0
	v_mov_b32_e32 v0, 0x1400
	v_mov_b32_e32 v1, 1
	global_atomic_add v4, v0, v1, s[6:7] sc0
	s_mov_b32 s13, 0
	s_add_u32 s14, s84, 0x2480
	s_addc_u32 s15, s85, 0
	s_waitcnt lgkmcnt(0)
	v_readfirstlane_b32 s10, v2
	v_readfirstlane_b32 s11, v3
	v_mov_b32_e32 v0, 0
	s_nop 3
	s_mul_i32 s10, s10, 8
	s_mul_i32 s11, s11, 7
	s_waitcnt vmcnt(0)
	v_readfirstlane_b32 s12, v4
	s_nop 3
	s_add_u32 s12, s12, 1
	s_cmp_lg_u32 s12, s10
	s_cbranch_scc1 .Lgb8_poll
	buffer_wbl2 sc1
	s_waitcnt vmcnt(0)
	global_atomic_add v0, v1, s[14:15] offset:0
	global_atomic_add v0, v1, s[14:15] offset:256
	global_atomic_add v0, v1, s[14:15] offset:512
	global_atomic_add v0, v1, s[14:15] offset:768
	global_atomic_add v0, v1, s[14:15] offset:1024
	global_atomic_add v0, v1, s[14:15] offset:1280
	global_atomic_add v0, v1, s[14:15] offset:1536
	global_atomic_add v0, v1, s[14:15] offset:1792
	global_atomic_add v0, v1, s[14:15] offset:2048
	global_atomic_add v0, v1, s[14:15] offset:2304
	global_atomic_add v0, v1, s[14:15] offset:2560
	global_atomic_add v0, v1, s[14:15] offset:2816
	global_atomic_add v0, v1, s[14:15] offset:3072
	global_atomic_add v0, v1, s[14:15] offset:3328
	global_atomic_add v0, v1, s[14:15] offset:3584
	global_atomic_add v0, v1, s[14:15] offset:3840
	v_mov_b32_e32 v0, 0x2480

.Lr9_end:
.LBB0_1021:
	s_cmp_lt_i32 s61, 10
	s_cbranch_scc1 .LBB0_1075
	s_waitcnt vmcnt(0)
	s_barrier
	v_readfirstlane_b32 s2, v162
	s_and_b32 s3, s58, 7
	s_lshl_b32 s3, s3, 8
	s_bfe_u32 s6, s58, 0x30003
	s_lshl_b32 s6, s6, 2
	s_add_u32 s3, s3, s6
	s_add_u32 s3, s3, 0x3820
	s_add_u32 s6, s84, s3
	s_addc_u32 s7, s85, 0
	s_cmp_lg_u32 s2, 0
	s_cbranch_scc1 .Lgs9_wait
	s_mov_b64 s[8:9], exec
	s_mov_b64 exec, 1
	v_mov_b32_e32 v0, 0
	v_mov_b32_e32 v1, 1
	s_mov_b32 s10, 0
	global_atomic_add v0, v1, s[6:7]
	s_sleep 40

.LBB0_1079:
	s_or_b64 exec, exec, s[10:11]
	s_cmp_lt_u32 s61, 11
	s_cbranch_scc1 .LBB0_1133
	s_waitcnt vmcnt(0) lgkmcnt(0)
	s_barrier
	v_readfirstlane_b32 s2, v162
	s_lshl_b32 s3, s33, 8
	s_add_u32 s6, s84, s3
	s_addc_u32 s7, s85, 0
	s_cmp_lg_u32 s2, 0
	s_cbranch_scc1 .Lgb10_wait
	s_mov_b64 s[8:9], exec
	s_mov_b64 exec, 1
	v_mov_b32_e32 v0, 0x12000
	ds_read_b64 v[2:3], v0
	v_mov_b32_e32 v0, 0x1400
	v_mov_b32_e32 v1, 1
	global_atomic_add v4, v0, v1, s[6:7] sc0
	s_mov_b32 s13, 0
	s_add_u32 s14, s84, 0x2480
	s_addc_u32 s15, s85, 0
	s_waitcnt lgkmcnt(0)
	v_readfirstlane_b32 s10, v2
	v_readfirstlane_b32 s11, v3
	v_mov_b32_e32 v0, 0
	s_nop 3
	s_mul_i32 s10, s10, 9
	s_mul_i32 s11, s11, 8
	s_waitcnt vmcnt(0)
	v_readfirstlane_b32 s12, v4
	s_nop 3
	s_add_u32 s12, s12, 1
	s_cmp_lg_u32 s12, s10
	s_cbranch_scc1 .Lgb10_poll
	buffer_wbl2 sc1
	s_waitcnt vmcnt(0)
	global_atomic_add v0, v1, s[14:15] offset:0
	global_atomic_add v0, v1, s[14:15] offset:256
	global_atomic_add v0, v1, s[14:15] offset:512
	global_atomic_add v0, v1, s[14:15] offset:768
	global_atomic_add v0, v1, s[14:15] offset:1024
	global_atomic_add v0, v1, s[14:15] offset:1280
	global_atomic_add v0, v1, s[14:15] offset:1536
	global_atomic_add v0, v1, s[14:15] offset:1792
	global_atomic_add v0, v1, s[14:15] offset:2048
	global_atomic_add v0, v1, s[14:15] offset:2304
	global_atomic_add v0, v1, s[14:15] offset:2560
	global_atomic_add v0, v1, s[14:15] offset:2816
	global_atomic_add v0, v1, s[14:15] offset:3072
	global_atomic_add v0, v1, s[14:15] offset:3328
	global_atomic_add v0, v1, s[14:15] offset:3584
	global_atomic_add v0, v1, s[14:15] offset:3840
	v_mov_b32_e32 v0, 0x2480

.LBB0_1142:
	s_cmp_lt_i32 s61, 12
	s_cbranch_scc1 .LBB0_1196
	s_waitcnt vmcnt(0) lgkmcnt(0)
	s_barrier
	v_readfirstlane_b32 s2, v162
	s_lshl_b32 s3, s33, 8
	s_add_u32 s6, s84, s3
	s_addc_u32 s7, s85, 0
	s_cmp_lg_u32 s2, 0
	s_cbranch_scc1 .Lgb11_wait
	s_mov_b64 s[8:9], exec
	s_mov_b64 exec, 1
	v_mov_b32_e32 v0, 0x12000
	ds_read_b64 v[2:3], v0
	v_mov_b32_e32 v0, 0x1400
	v_mov_b32_e32 v1, 1
	global_atomic_add v4, v0, v1, s[6:7] sc0
	s_mov_b32 s13, 0
	s_add_u32 s14, s84, 0x2480
	s_addc_u32 s15, s85, 0
	s_waitcnt lgkmcnt(0)
	v_readfirstlane_b32 s10, v2
	v_readfirstlane_b32 s11, v3
	v_mov_b32_e32 v0, 0
	s_nop 3
	s_mul_i32 s10, s10, 10
	s_mul_i32 s11, s11, 9
	s_waitcnt vmcnt(0)
	v_readfirstlane_b32 s12, v4
	s_nop 3
	s_add_u32 s12, s12, 1
	s_cmp_lg_u32 s12, s10
	s_cbranch_scc1 .Lgb11_poll
	buffer_wbl2 sc1
	s_waitcnt vmcnt(0)
	global_atomic_add v0, v1, s[14:15] offset:0
	global_atomic_add v0, v1, s[14:15] offset:256
	global_atomic_add v0, v1, s[14:15] offset:512
	global_atomic_add v0, v1, s[14:15] offset:768
	global_atomic_add v0, v1, s[14:15] offset:1024
	global_atomic_add v0, v1, s[14:15] offset:1280
	global_atomic_add v0, v1, s[14:15] offset:1536
	global_atomic_add v0, v1, s[14:15] offset:1792
	global_atomic_add v0, v1, s[14:15] offset:2048
	global_atomic_add v0, v1, s[14:15] offset:2304
	global_atomic_add v0, v1, s[14:15] offset:2560
	global_atomic_add v0, v1, s[14:15] offset:2816
	global_atomic_add v0, v1, s[14:15] offset:3072
	global_atomic_add v0, v1, s[14:15] offset:3328
	global_atomic_add v0, v1, s[14:15] offset:3584
	global_atomic_add v0, v1, s[14:15] offset:3840
	v_mov_b32_e32 v0, 0x2480

.LBB0_1206:
	s_cmp_lt_i32 s61, 13
	s_cbranch_scc1 .LBB0_1260
	s_waitcnt vmcnt(0) lgkmcnt(0)
	s_barrier
	v_readfirstlane_b32 s2, v162
	s_lshl_b32 s3, s33, 8
	s_add_u32 s6, s84, s3
	s_addc_u32 s7, s85, 0
	s_cmp_lg_u32 s2, 0
	s_cbranch_scc1 .Lgb12_wait
	s_mov_b64 s[8:9], exec
	s_mov_b64 exec, 1
	v_mov_b32_e32 v0, 0x12000
	ds_read_b64 v[2:3], v0
	v_mov_b32_e32 v0, 0x1400
	v_mov_b32_e32 v1, 1
	global_atomic_add v4, v0, v1, s[6:7] sc0
	s_mov_b32 s13, 0
	s_add_u32 s14, s84, 0x2480
	s_addc_u32 s15, s85, 0
	s_waitcnt lgkmcnt(0)
	v_readfirstlane_b32 s10, v2
	v_readfirstlane_b32 s11, v3
	v_mov_b32_e32 v0, 0
	s_nop 3
	s_mul_i32 s10, s10, 11
	s_mul_i32 s11, s11, 10
	s_waitcnt vmcnt(0)
	v_readfirstlane_b32 s12, v4
	s_nop 3
	s_add_u32 s12, s12, 1
	s_cmp_lg_u32 s12, s10
	s_cbranch_scc1 .Lgb12_poll
	buffer_wbl2 sc1
	s_waitcnt vmcnt(0)
	global_atomic_add v0, v1, s[14:15] offset:0
	global_atomic_add v0, v1, s[14:15] offset:256
	global_atomic_add v0, v1, s[14:15] offset:512
	global_atomic_add v0, v1, s[14:15] offset:768
	global_atomic_add v0, v1, s[14:15] offset:1024
	global_atomic_add v0, v1, s[14:15] offset:1280
	global_atomic_add v0, v1, s[14:15] offset:1536
	global_atomic_add v0, v1, s[14:15] offset:1792
	global_atomic_add v0, v1, s[14:15] offset:2048
	global_atomic_add v0, v1, s[14:15] offset:2304
	global_atomic_add v0, v1, s[14:15] offset:2560
	global_atomic_add v0, v1, s[14:15] offset:2816
	global_atomic_add v0, v1, s[14:15] offset:3072
	global_atomic_add v0, v1, s[14:15] offset:3328
	global_atomic_add v0, v1, s[14:15] offset:3584
	global_atomic_add v0, v1, s[14:15] offset:3840
	v_mov_b32_e32 v0, 0x2480

.Lr13_end:
.LBB0_1274:
	s_cmp_lt_i32 s61, 14
	s_cbranch_scc1 .LBB0_1328
	s_waitcnt vmcnt(0)
	s_barrier
	v_readfirstlane_b32 s2, v162
	s_and_b32 s3, s58, 7
	s_lshl_b32 s3, s3, 8
	s_bfe_u32 s6, s58, 0x30003
	s_lshl_b32 s6, s6, 2
	s_add_u32 s3, s3, s6
	s_add_u32 s3, s3, 0x3840
	s_add_u32 s6, s84, s3
	s_addc_u32 s7, s85, 0
	s_cmp_lg_u32 s2, 0
	s_cbranch_scc1 .Lgs13_wait
	s_mov_b64 s[8:9], exec
	s_mov_b64 exec, 1
	v_mov_b32_e32 v0, 0
	v_mov_b32_e32 v1, 1
	s_mov_b32 s10, 0
	global_atomic_add v0, v1, s[6:7]
	s_sleep 40

.LBB0_1332:
	s_or_b64 exec, exec, s[10:11]
	s_cmp_lt_u32 s61, 15
	s_cbranch_scc1 .LBB0_1386
	s_waitcnt vmcnt(0) lgkmcnt(0)
	s_barrier
	v_readfirstlane_b32 s2, v162
	s_lshl_b32 s3, s33, 8
	s_add_u32 s6, s84, s3
	s_addc_u32 s7, s85, 0
	s_cmp_lg_u32 s2, 0
	s_cbranch_scc1 .Lgb14_wait
	s_mov_b64 s[8:9], exec
	s_mov_b64 exec, 1
	v_mov_b32_e32 v0, 0x12000
	ds_read_b64 v[2:3], v0
	v_mov_b32_e32 v0, 0x1400
	v_mov_b32_e32 v1, 1
	global_atomic_add v4, v0, v1, s[6:7] sc0
	s_mov_b32 s13, 0
	s_add_u32 s14, s84, 0x2480
	s_addc_u32 s15, s85, 0
	s_waitcnt lgkmcnt(0)
	v_readfirstlane_b32 s10, v2
	v_readfirstlane_b32 s11, v3
	v_mov_b32_e32 v0, 0
	s_nop 3
	s_mul_i32 s10, s10, 12
	s_mul_i32 s11, s11, 11
	s_waitcnt vmcnt(0)
	v_readfirstlane_b32 s12, v4
	s_nop 3
	s_add_u32 s12, s12, 1
	s_cmp_lg_u32 s12, s10
	s_cbranch_scc1 .Lgb14_poll
	buffer_wbl2 sc1
	s_waitcnt vmcnt(0)
	global_atomic_add v0, v1, s[14:15] offset:0
	global_atomic_add v0, v1, s[14:15] offset:256
	global_atomic_add v0, v1, s[14:15] offset:512
	global_atomic_add v0, v1, s[14:15] offset:768
	global_atomic_add v0, v1, s[14:15] offset:1024
	global_atomic_add v0, v1, s[14:15] offset:1280
	global_atomic_add v0, v1, s[14:15] offset:1536
	global_atomic_add v0, v1, s[14:15] offset:1792
	global_atomic_add v0, v1, s[14:15] offset:2048
	global_atomic_add v0, v1, s[14:15] offset:2304
	global_atomic_add v0, v1, s[14:15] offset:2560
	global_atomic_add v0, v1, s[14:15] offset:2816
	global_atomic_add v0, v1, s[14:15] offset:3072
	global_atomic_add v0, v1, s[14:15] offset:3328
	global_atomic_add v0, v1, s[14:15] offset:3584
	global_atomic_add v0, v1, s[14:15] offset:3840
	v_mov_b32_e32 v0, 0x2480

.Lf15_end:
.LBB0_1396:
	s_cmp_lt_i32 s61, 16
	s_cbranch_scc1 .LBB0_1450
	s_waitcnt vmcnt(0) lgkmcnt(0)
	s_barrier
	v_readfirstlane_b32 s2, v162
	s_lshl_b32 s3, s33, 8
	s_add_u32 s6, s84, s3
	s_addc_u32 s7, s85, 0
	s_cmp_lg_u32 s2, 0
	s_cbranch_scc1 .Lgb15_wait
	s_mov_b64 s[8:9], exec
	s_mov_b64 exec, 1
	v_mov_b32_e32 v0, 0x12000
	ds_read_b64 v[2:3], v0
	v_mov_b32_e32 v0, 0x1400
	v_mov_b32_e32 v1, 1
	global_atomic_add v4, v0, v1, s[6:7] sc0
	s_mov_b32 s13, 0
	s_add_u32 s14, s84, 0x2480
	s_addc_u32 s15, s85, 0
	s_waitcnt lgkmcnt(0)
	v_readfirstlane_b32 s10, v2
	v_readfirstlane_b32 s11, v3
	v_mov_b32_e32 v0, 0
	s_nop 3
	s_mul_i32 s10, s10, 13
	s_mul_i32 s11, s11, 12
	s_waitcnt vmcnt(0)
	v_readfirstlane_b32 s12, v4
	s_nop 3
	s_add_u32 s12, s12, 1
	s_cmp_lg_u32 s12, s10
	s_cbranch_scc1 .Lgb15_poll
	buffer_wbl2 sc1
	s_waitcnt vmcnt(0)
	global_atomic_add v0, v1, s[14:15] offset:0
	global_atomic_add v0, v1, s[14:15] offset:256
	global_atomic_add v0, v1, s[14:15] offset:512
	global_atomic_add v0, v1, s[14:15] offset:768
	global_atomic_add v0, v1, s[14:15] offset:1024
	global_atomic_add v0, v1, s[14:15] offset:1280
	global_atomic_add v0, v1, s[14:15] offset:1536
	global_atomic_add v0, v1, s[14:15] offset:1792
	global_atomic_add v0, v1, s[14:15] offset:2048
	global_atomic_add v0, v1, s[14:15] offset:2304
	global_atomic_add v0, v1, s[14:15] offset:2560
	global_atomic_add v0, v1, s[14:15] offset:2816
	global_atomic_add v0, v1, s[14:15] offset:3072
	global_atomic_add v0, v1, s[14:15] offset:3328
	global_atomic_add v0, v1, s[14:15] offset:3584
	global_atomic_add v0, v1, s[14:15] offset:3840
	v_mov_b32_e32 v0, 0x2480

.Lr16_end:
.LBB0_1456:
	s_cmp_lt_i32 s61, 17
	s_cbranch_scc1 .LBB0_1510
	s_waitcnt vmcnt(0)
	s_barrier
	v_readfirstlane_b32 s2, v162
	s_and_b32 s3, s58, 7
	s_lshl_b32 s3, s3, 8
	s_bfe_u32 s6, s58, 0x30003
	s_lshl_b32 s6, s6, 2
	s_add_u32 s3, s3, s6
	s_add_u32 s3, s3, 0x3860
	s_add_u32 s6, s84, s3
	s_addc_u32 s7, s85, 0
	s_cmp_lg_u32 s2, 0
	s_cbranch_scc1 .Lgs16_wait
	s_mov_b64 s[8:9], exec
	s_mov_b64 exec, 1
	v_mov_b32_e32 v0, 0
	v_mov_b32_e32 v1, 1
	s_mov_b32 s10, 0
	global_atomic_add v0, v1, s[6:7]
	s_sleep 40

.LBB0_1519:
	s_or_b64 exec, exec, s[4:5]
	s_cmp_lt_u32 s61, 18
	s_cbranch_scc1 .LBB0_1573
	s_waitcnt vmcnt(0) lgkmcnt(0)
	s_barrier
	v_readfirstlane_b32 s2, v162
	s_lshl_b32 s3, s33, 8
	s_add_u32 s6, s84, s3
	s_addc_u32 s7, s85, 0
	s_cmp_lg_u32 s2, 0
	s_cbranch_scc1 .Lgb17_wait
	s_mov_b64 s[8:9], exec
	s_mov_b64 exec, 1
	v_mov_b32_e32 v0, 0x12000
	ds_read_b64 v[2:3], v0
	v_mov_b32_e32 v0, 0x1400
	v_mov_b32_e32 v1, 1
	global_atomic_add v4, v0, v1, s[6:7] sc0
	s_mov_b32 s13, 0
	s_add_u32 s14, s84, 0x2480
	s_addc_u32 s15, s85, 0
	s_waitcnt lgkmcnt(0)
	v_readfirstlane_b32 s10, v2
	v_readfirstlane_b32 s11, v3
	v_mov_b32_e32 v0, 0
	s_nop 3
	s_mul_i32 s10, s10, 14
	s_mul_i32 s11, s11, 13
	s_waitcnt vmcnt(0)
	v_readfirstlane_b32 s12, v4
	s_nop 3
	s_add_u32 s12, s12, 1
	s_cmp_lg_u32 s12, s10
	s_cbranch_scc1 .Lgb17_poll
	buffer_wbl2 sc1
	s_waitcnt vmcnt(0)
	global_atomic_add v0, v1, s[14:15] offset:0
	global_atomic_add v0, v1, s[14:15] offset:256
	global_atomic_add v0, v1, s[14:15] offset:512
	global_atomic_add v0, v1, s[14:15] offset:768
	global_atomic_add v0, v1, s[14:15] offset:1024
	global_atomic_add v0, v1, s[14:15] offset:1280
	global_atomic_add v0, v1, s[14:15] offset:1536
	global_atomic_add v0, v1, s[14:15] offset:1792
	global_atomic_add v0, v1, s[14:15] offset:2048
	global_atomic_add v0, v1, s[14:15] offset:2304
	global_atomic_add v0, v1, s[14:15] offset:2560
	global_atomic_add v0, v1, s[14:15] offset:2816
	global_atomic_add v0, v1, s[14:15] offset:3072
	global_atomic_add v0, v1, s[14:15] offset:3328
	global_atomic_add v0, v1, s[14:15] offset:3584
	global_atomic_add v0, v1, s[14:15] offset:3840
	v_mov_b32_e32 v0, 0x2480

.LBB0_1791:
	s_cmp_lt_i32 s61, 19
	s_mov_b64 s[84:85], s[76:77]
	s_cbranch_scc1 .LBB0_1845
	s_waitcnt vmcnt(0) lgkmcnt(0)
	s_barrier
	v_readfirstlane_b32 s2, v162
	s_lshl_b32 s3, s33, 8
	s_add_u32 s6, s84, s3
	s_addc_u32 s7, s85, 0
	s_cmp_lg_u32 s2, 0
	s_cbranch_scc1 .Lgb18_wait
	s_mov_b64 s[8:9], exec
	s_mov_b64 exec, 1
	v_mov_b32_e32 v0, 0x12000
	ds_read_b64 v[2:3], v0
	v_mov_b32_e32 v0, 0x1400
	v_mov_b32_e32 v1, 1
	global_atomic_add v4, v0, v1, s[6:7] sc0
	s_mov_b32 s13, 0
	s_add_u32 s14, s84, 0x2480
	s_addc_u32 s15, s85, 0
	s_waitcnt lgkmcnt(0)
	v_readfirstlane_b32 s10, v2
	v_readfirstlane_b32 s11, v3
	v_mov_b32_e32 v0, 0
	s_nop 3
	s_mul_i32 s10, s10, 15
	s_mul_i32 s11, s11, 14
	s_waitcnt vmcnt(0)
	v_readfirstlane_b32 s12, v4
	s_nop 3
	s_add_u32 s12, s12, 1
	s_cmp_lg_u32 s12, s10
	s_cbranch_scc1 .Lgb18_poll
	buffer_wbl2 sc1
	s_waitcnt vmcnt(0)
	global_atomic_add v0, v1, s[14:15] offset:0
	global_atomic_add v0, v1, s[14:15] offset:256
	global_atomic_add v0, v1, s[14:15] offset:512
	global_atomic_add v0, v1, s[14:15] offset:768
	global_atomic_add v0, v1, s[14:15] offset:1024
	global_atomic_add v0, v1, s[14:15] offset:1280
	global_atomic_add v0, v1, s[14:15] offset:1536
	global_atomic_add v0, v1, s[14:15] offset:1792
	global_atomic_add v0, v1, s[14:15] offset:2048
	global_atomic_add v0, v1, s[14:15] offset:2304
	global_atomic_add v0, v1, s[14:15] offset:2560
	global_atomic_add v0, v1, s[14:15] offset:2816
	global_atomic_add v0, v1, s[14:15] offset:3072
	global_atomic_add v0, v1, s[14:15] offset:3328
	global_atomic_add v0, v1, s[14:15] offset:3584
	global_atomic_add v0, v1, s[14:15] offset:3840
	v_mov_b32_e32 v0, 0x2480

.LBB0_1864:
	s_or_b64 exec, exec, s[4:5]
	s_cmp_lt_i32 s61, 20
	s_cbranch_scc1 .LBB0_1918
	s_waitcnt vmcnt(0) lgkmcnt(0)
	s_barrier
	v_readfirstlane_b32 s2, v162
	s_lshl_b32 s3, s33, 8
	s_add_u32 s6, s84, s3
	s_addc_u32 s7, s85, 0
	s_cmp_lg_u32 s2, 0
	s_cbranch_scc1 .Lgb19_wait
	s_mov_b64 s[8:9], exec
	s_mov_b64 exec, 1
	v_mov_b32_e32 v0, 0x12000
	ds_read_b64 v[2:3], v0
	v_mov_b32_e32 v0, 0x1400
	v_mov_b32_e32 v1, 1
	global_atomic_add v4, v0, v1, s[6:7] sc0
	s_mov_b32 s13, 0
	s_add_u32 s14, s84, 0x2480
	s_addc_u32 s15, s85, 0
	s_waitcnt lgkmcnt(0)
	v_readfirstlane_b32 s10, v2
	v_readfirstlane_b32 s11, v3
	v_mov_b32_e32 v0, 0
	s_nop 3
	s_mul_i32 s10, s10, 16
	s_mul_i32 s11, s11, 15
	s_waitcnt vmcnt(0)
	v_readfirstlane_b32 s12, v4
	s_nop 3
	s_add_u32 s12, s12, 1
	s_cmp_lg_u32 s12, s10
	s_cbranch_scc1 .Lgb19_poll
	buffer_wbl2 sc1
	s_waitcnt vmcnt(0)
	global_atomic_add v0, v1, s[14:15] offset:0
	global_atomic_add v0, v1, s[14:15] offset:256
	global_atomic_add v0, v1, s[14:15] offset:512
	global_atomic_add v0, v1, s[14:15] offset:768
	global_atomic_add v0, v1, s[14:15] offset:1024
	global_atomic_add v0, v1, s[14:15] offset:1280
	global_atomic_add v0, v1, s[14:15] offset:1536
	global_atomic_add v0, v1, s[14:15] offset:1792
	global_atomic_add v0, v1, s[14:15] offset:2048
	global_atomic_add v0, v1, s[14:15] offset:2304
	global_atomic_add v0, v1, s[14:15] offset:2560
	global_atomic_add v0, v1, s[14:15] offset:2816
	global_atomic_add v0, v1, s[14:15] offset:3072
	global_atomic_add v0, v1, s[14:15] offset:3328
	global_atomic_add v0, v1, s[14:15] offset:3584
	global_atomic_add v0, v1, s[14:15] offset:3840
	v_mov_b32_e32 v0, 0x2480

.LBB0_2180:
	s_cmp_lt_i32 s61, 21
	s_cbranch_scc1 .LBB0_2234
	s_waitcnt vmcnt(0) lgkmcnt(0)
	s_barrier
	v_readfirstlane_b32 s2, v162
	s_lshl_b32 s3, s33, 8
	s_add_u32 s6, s84, s3
	s_addc_u32 s7, s85, 0
	s_cmp_lg_u32 s2, 0
	s_cbranch_scc1 .Lgb20_wait
	s_mov_b64 s[8:9], exec
	s_mov_b64 exec, 1
	v_mov_b32_e32 v0, 0x12000
	ds_read_b64 v[2:3], v0
	v_mov_b32_e32 v0, 0x1400
	v_mov_b32_e32 v1, 1
	global_atomic_add v4, v0, v1, s[6:7] sc0
	s_mov_b32 s13, 0
	s_add_u32 s14, s84, 0x2480
	s_addc_u32 s15, s85, 0
	s_waitcnt lgkmcnt(0)
	v_readfirstlane_b32 s10, v2
	v_readfirstlane_b32 s11, v3
	v_mov_b32_e32 v0, 0
	s_nop 3
	s_mul_i32 s10, s10, 17
	s_mul_i32 s11, s11, 16
	s_waitcnt vmcnt(0)
	v_readfirstlane_b32 s12, v4
	s_nop 3
	s_add_u32 s12, s12, 1
	s_cmp_lg_u32 s12, s10
	s_cbranch_scc1 .Lgb20_poll
	buffer_wbl2 sc1
	s_waitcnt vmcnt(0)
	global_atomic_add v0, v1, s[14:15] offset:0
	global_atomic_add v0, v1, s[14:15] offset:256
	global_atomic_add v0, v1, s[14:15] offset:512
	global_atomic_add v0, v1, s[14:15] offset:768
	global_atomic_add v0, v1, s[14:15] offset:1024
	global_atomic_add v0, v1, s[14:15] offset:1280
	global_atomic_add v0, v1, s[14:15] offset:1536
	global_atomic_add v0, v1, s[14:15] offset:1792
	global_atomic_add v0, v1, s[14:15] offset:2048
	global_atomic_add v0, v1, s[14:15] offset:2304
	global_atomic_add v0, v1, s[14:15] offset:2560
	global_atomic_add v0, v1, s[14:15] offset:2816
	global_atomic_add v0, v1, s[14:15] offset:3072
	global_atomic_add v0, v1, s[14:15] offset:3328
	global_atomic_add v0, v1, s[14:15] offset:3584
	global_atomic_add v0, v1, s[14:15] offset:3840
	v_mov_b32_e32 v0, 0x2480

.LBB0_2238:
	s_or_b64 exec, exec, s[6:7]
	s_cmp_lt_u32 s61, 22
	s_cbranch_scc1 .LBB0_2292
	s_waitcnt vmcnt(0) lgkmcnt(0)
	s_barrier
	v_readfirstlane_b32 s2, v162
	s_lshl_b32 s3, s33, 8
	s_add_u32 s6, s84, s3
	s_addc_u32 s7, s85, 0
	s_cmp_lg_u32 s2, 0
	s_cbranch_scc1 .Lgb21_wait
	s_mov_b64 s[8:9], exec
	s_mov_b64 exec, 1
	v_mov_b32_e32 v0, 0x12000
	ds_read_b64 v[2:3], v0
	v_mov_b32_e32 v0, 0x1400
	v_mov_b32_e32 v1, 1
	global_atomic_add v4, v0, v1, s[6:7] sc0
	s_mov_b32 s13, 0
	s_add_u32 s14, s84, 0x2480
	s_addc_u32 s15, s85, 0
	s_waitcnt lgkmcnt(0)
	v_readfirstlane_b32 s10, v2
	v_readfirstlane_b32 s11, v3
	v_mov_b32_e32 v0, 0
	s_nop 3
	s_mul_i32 s10, s10, 18
	s_mul_i32 s11, s11, 17
	s_waitcnt vmcnt(0)
	v_readfirstlane_b32 s12, v4
	s_nop 3
	s_add_u32 s12, s12, 1
	s_cmp_lg_u32 s12, s10
	s_cbranch_scc1 .Lgb21_poll
	buffer_wbl2 sc1
	s_waitcnt vmcnt(0)
	global_atomic_add v0, v1, s[14:15] offset:0
	global_atomic_add v0, v1, s[14:15] offset:256
	global_atomic_add v0, v1, s[14:15] offset:512
	global_atomic_add v0, v1, s[14:15] offset:768
	global_atomic_add v0, v1, s[14:15] offset:1024
	global_atomic_add v0, v1, s[14:15] offset:1280
	global_atomic_add v0, v1, s[14:15] offset:1536
	global_atomic_add v0, v1, s[14:15] offset:1792
	global_atomic_add v0, v1, s[14:15] offset:2048
	global_atomic_add v0, v1, s[14:15] offset:2304
	global_atomic_add v0, v1, s[14:15] offset:2560
	global_atomic_add v0, v1, s[14:15] offset:2816
	global_atomic_add v0, v1, s[14:15] offset:3072
	global_atomic_add v0, v1, s[14:15] offset:3328
	global_atomic_add v0, v1, s[14:15] offset:3584
	global_atomic_add v0, v1, s[14:15] offset:3840
	v_mov_b32_e32 v0, 0x2480

.Lr22_end:
.LBB0_2298:
	s_cmp_lt_i32 s61, 23
	s_cbranch_scc1 .LBB0_2352
	s_waitcnt vmcnt(0)
	s_barrier
	v_readfirstlane_b32 s2, v162
	s_and_b32 s3, s58, 7
	s_lshl_b32 s3, s3, 8
	s_bfe_u32 s6, s58, 0x30003
	s_lshl_b32 s6, s6, 2
	s_add_u32 s3, s3, s6
	s_add_u32 s3, s3, 0x3880
	s_add_u32 s6, s84, s3
	s_addc_u32 s7, s85, 0
	s_cmp_lg_u32 s2, 0
	s_cbranch_scc1 .Lgs22_wait
	s_mov_b64 s[8:9], exec
	s_mov_b64 exec, 1
	v_mov_b32_e32 v0, 0
	v_mov_b32_e32 v1, 1
	s_mov_b32 s10, 0
	global_atomic_add v0, v1, s[6:7]
	s_sleep 40

.LBB0_2356:
	s_or_b64 exec, exec, s[10:11]
	s_cmp_lt_u32 s61, 24
	s_cbranch_scc1 .LBB0_2410
	s_waitcnt vmcnt(0) lgkmcnt(0)
	s_barrier
	v_readfirstlane_b32 s2, v162
	s_lshl_b32 s3, s33, 8
	s_add_u32 s6, s84, s3
	s_addc_u32 s7, s85, 0
	s_cmp_lg_u32 s2, 0
	s_cbranch_scc1 .Lgb23_wait
	s_mov_b64 s[8:9], exec
	s_mov_b64 exec, 1
	v_mov_b32_e32 v0, 0x12000
	ds_read_b64 v[2:3], v0
	v_mov_b32_e32 v0, 0x1400
	v_mov_b32_e32 v1, 1
	global_atomic_add v4, v0, v1, s[6:7] sc0
	s_mov_b32 s13, 0
	s_add_u32 s14, s84, 0x2480
	s_addc_u32 s15, s85, 0
	s_waitcnt lgkmcnt(0)
	v_readfirstlane_b32 s10, v2
	v_readfirstlane_b32 s11, v3
	v_mov_b32_e32 v0, 0
	s_nop 3
	s_mul_i32 s10, s10, 19
	s_mul_i32 s11, s11, 18
	s_waitcnt vmcnt(0)
	v_readfirstlane_b32 s12, v4
	s_nop 3
	s_add_u32 s12, s12, 1
	s_cmp_lg_u32 s12, s10
	s_cbranch_scc1 .Lgb23_poll
	buffer_wbl2 sc1
	s_waitcnt vmcnt(0)
	global_atomic_add v0, v1, s[14:15] offset:0
	global_atomic_add v0, v1, s[14:15] offset:256
	global_atomic_add v0, v1, s[14:15] offset:512
	global_atomic_add v0, v1, s[14:15] offset:768
	global_atomic_add v0, v1, s[14:15] offset:1024
	global_atomic_add v0, v1, s[14:15] offset:1280
	global_atomic_add v0, v1, s[14:15] offset:1536
	global_atomic_add v0, v1, s[14:15] offset:1792
	global_atomic_add v0, v1, s[14:15] offset:2048
	global_atomic_add v0, v1, s[14:15] offset:2304
	global_atomic_add v0, v1, s[14:15] offset:2560
	global_atomic_add v0, v1, s[14:15] offset:2816
	global_atomic_add v0, v1, s[14:15] offset:3072
	global_atomic_add v0, v1, s[14:15] offset:3328
	global_atomic_add v0, v1, s[14:15] offset:3584
	global_atomic_add v0, v1, s[14:15] offset:3840
	v_mov_b32_e32 v0, 0x2480

.Lf24_end:
.LBB0_2420:
	s_cmp_lt_i32 s61, 25
	s_cbranch_scc1 .LBB0_2474
	s_waitcnt vmcnt(0) lgkmcnt(0)
	s_barrier
	v_readfirstlane_b32 s2, v162
	s_lshl_b32 s3, s33, 8
	s_add_u32 s6, s84, s3
	s_addc_u32 s7, s85, 0
	s_cmp_lg_u32 s2, 0
	s_cbranch_scc1 .Lgb24_wait
	s_mov_b64 s[8:9], exec
	s_mov_b64 exec, 1
	v_mov_b32_e32 v0, 0x12000
	ds_read_b64 v[2:3], v0
	v_mov_b32_e32 v0, 0x1400
	v_mov_b32_e32 v1, 1
	global_atomic_add v4, v0, v1, s[6:7] sc0
	s_mov_b32 s13, 0
	s_add_u32 s14, s84, 0x2480
	s_addc_u32 s15, s85, 0
	s_waitcnt lgkmcnt(0)
	v_readfirstlane_b32 s10, v2
	v_readfirstlane_b32 s11, v3
	v_mov_b32_e32 v0, 0
	s_nop 3
	s_mul_i32 s10, s10, 20
	s_mul_i32 s11, s11, 19
	s_waitcnt vmcnt(0)
	v_readfirstlane_b32 s12, v4
	s_nop 3
	s_add_u32 s12, s12, 1
	s_cmp_lg_u32 s12, s10
	s_cbranch_scc1 .Lgb24_poll
	buffer_wbl2 sc1
	s_waitcnt vmcnt(0)
	global_atomic_add v0, v1, s[14:15] offset:0
	global_atomic_add v0, v1, s[14:15] offset:256
	global_atomic_add v0, v1, s[14:15] offset:512
	global_atomic_add v0, v1, s[14:15] offset:768
	global_atomic_add v0, v1, s[14:15] offset:1024
	global_atomic_add v0, v1, s[14:15] offset:1280
	global_atomic_add v0, v1, s[14:15] offset:1536
	global_atomic_add v0, v1, s[14:15] offset:1792
	global_atomic_add v0, v1, s[14:15] offset:2048
	global_atomic_add v0, v1, s[14:15] offset:2304
	global_atomic_add v0, v1, s[14:15] offset:2560
	global_atomic_add v0, v1, s[14:15] offset:2816
	global_atomic_add v0, v1, s[14:15] offset:3072
	global_atomic_add v0, v1, s[14:15] offset:3328
	global_atomic_add v0, v1, s[14:15] offset:3584
	global_atomic_add v0, v1, s[14:15] offset:3840
	v_mov_b32_e32 v0, 0x2480

.Lr25_end:
.LBB0_2480:
	s_cmp_lt_i32 s61, 26
	s_cbranch_scc1 .LBB0_2534
	s_waitcnt vmcnt(0)
	s_barrier
	v_readfirstlane_b32 s2, v162
	s_and_b32 s3, s58, 7
	s_lshl_b32 s3, s3, 8
	s_bfe_u32 s6, s58, 0x30003
	s_lshl_b32 s6, s6, 2
	s_add_u32 s3, s3, s6
	s_add_u32 s3, s3, 0x38a0
	s_add_u32 s6, s84, s3
	s_addc_u32 s7, s85, 0
	s_cmp_lg_u32 s2, 0
	s_cbranch_scc1 .Lgs25_wait
	s_mov_b64 s[8:9], exec
	s_mov_b64 exec, 1
	v_mov_b32_e32 v0, 0
	v_mov_b32_e32 v1, 1
	s_mov_b32 s10, 0
	global_atomic_add v0, v1, s[6:7]
	s_sleep 40

.LBB0_2538:
	s_or_b64 exec, exec, s[10:11]
	s_cmp_lt_u32 s61, 27
	s_cbranch_scc1 .LBB0_2592
	s_waitcnt vmcnt(0) lgkmcnt(0)
	s_barrier
	v_readfirstlane_b32 s2, v162
	s_lshl_b32 s3, s33, 8
	s_add_u32 s6, s84, s3
	s_addc_u32 s7, s85, 0
	s_cmp_lg_u32 s2, 0
	s_cbranch_scc1 .Lgb26_wait
	s_mov_b64 s[8:9], exec
	s_mov_b64 exec, 1
	v_mov_b32_e32 v0, 0x12000
	ds_read_b64 v[2:3], v0
	v_mov_b32_e32 v0, 0x1400
	v_mov_b32_e32 v1, 1
	global_atomic_add v4, v0, v1, s[6:7] sc0
	s_mov_b32 s13, 0
	s_add_u32 s14, s84, 0x2480
	s_addc_u32 s15, s85, 0
	s_waitcnt lgkmcnt(0)
	v_readfirstlane_b32 s10, v2
	v_readfirstlane_b32 s11, v3
	v_mov_b32_e32 v0, 0
	s_nop 3
	s_mul_i32 s10, s10, 21
	s_mul_i32 s11, s11, 20
	s_waitcnt vmcnt(0)
	v_readfirstlane_b32 s12, v4
	s_nop 3
	s_add_u32 s12, s12, 1
	s_cmp_lg_u32 s12, s10
	s_cbranch_scc1 .Lgb26_poll
	buffer_wbl2 sc1
	s_waitcnt vmcnt(0)
	global_atomic_add v0, v1, s[14:15] offset:0
	global_atomic_add v0, v1, s[14:15] offset:256
	global_atomic_add v0, v1, s[14:15] offset:512
	global_atomic_add v0, v1, s[14:15] offset:768
	global_atomic_add v0, v1, s[14:15] offset:1024
	global_atomic_add v0, v1, s[14:15] offset:1280
	global_atomic_add v0, v1, s[14:15] offset:1536
	global_atomic_add v0, v1, s[14:15] offset:1792
	global_atomic_add v0, v1, s[14:15] offset:2048
	global_atomic_add v0, v1, s[14:15] offset:2304
	global_atomic_add v0, v1, s[14:15] offset:2560
	global_atomic_add v0, v1, s[14:15] offset:2816
	global_atomic_add v0, v1, s[14:15] offset:3072
	global_atomic_add v0, v1, s[14:15] offset:3328
	global_atomic_add v0, v1, s[14:15] offset:3584
	global_atomic_add v0, v1, s[14:15] offset:3840
	v_mov_b32_e32 v0, 0x2480

.LBB0_2601:
	s_cmp_lt_i32 s61, 28
	s_cbranch_scc1 .LBB0_2655
	s_waitcnt vmcnt(0) lgkmcnt(0)
	s_barrier
	v_readfirstlane_b32 s2, v162
	s_lshl_b32 s3, s33, 8
	s_add_u32 s6, s84, s3
	s_addc_u32 s7, s85, 0
	s_cmp_lg_u32 s2, 0
	s_cbranch_scc1 .Lgb27_wait
	s_mov_b64 s[8:9], exec
	s_mov_b64 exec, 1
	v_mov_b32_e32 v0, 0x12000
	ds_read_b64 v[2:3], v0
	v_mov_b32_e32 v0, 0x1400
	v_mov_b32_e32 v1, 1
	global_atomic_add v4, v0, v1, s[6:7] sc0
	s_mov_b32 s13, 0
	s_add_u32 s14, s84, 0x2480
	s_addc_u32 s15, s85, 0
	s_waitcnt lgkmcnt(0)
	v_readfirstlane_b32 s10, v2
	v_readfirstlane_b32 s11, v3
	v_mov_b32_e32 v0, 0
	s_nop 3
	s_mul_i32 s10, s10, 22
	s_mul_i32 s11, s11, 21
	s_waitcnt vmcnt(0)
	v_readfirstlane_b32 s12, v4
	s_nop 3
	s_add_u32 s12, s12, 1
	s_cmp_lg_u32 s12, s10
	s_cbranch_scc1 .Lgb27_poll
	buffer_wbl2 sc1
	s_waitcnt vmcnt(0)
	global_atomic_add v0, v1, s[14:15] offset:0
	global_atomic_add v0, v1, s[14:15] offset:256
	global_atomic_add v0, v1, s[14:15] offset:512
	global_atomic_add v0, v1, s[14:15] offset:768
	global_atomic_add v0, v1, s[14:15] offset:1024
	global_atomic_add v0, v1, s[14:15] offset:1280
	global_atomic_add v0, v1, s[14:15] offset:1536
	global_atomic_add v0, v1, s[14:15] offset:1792
	global_atomic_add v0, v1, s[14:15] offset:2048
	global_atomic_add v0, v1, s[14:15] offset:2304
	global_atomic_add v0, v1, s[14:15] offset:2560
	global_atomic_add v0, v1, s[14:15] offset:2816
	global_atomic_add v0, v1, s[14:15] offset:3072
	global_atomic_add v0, v1, s[14:15] offset:3328
	global_atomic_add v0, v1, s[14:15] offset:3584
	global_atomic_add v0, v1, s[14:15] offset:3840
	v_mov_b32_e32 v0, 0x2480

.LBB0_2665:
	s_cmp_lt_i32 s61, 29
	s_cbranch_scc1 .LBB0_2719
	s_waitcnt vmcnt(0) lgkmcnt(0)
	s_barrier
	v_readfirstlane_b32 s2, v162
	s_lshl_b32 s3, s33, 8
	s_add_u32 s6, s84, s3
	s_addc_u32 s7, s85, 0
	s_cmp_lg_u32 s2, 0
	s_cbranch_scc1 .Lgb28_wait
	s_mov_b64 s[8:9], exec
	s_mov_b64 exec, 1
	v_mov_b32_e32 v0, 0x12000
	ds_read_b64 v[2:3], v0
	v_mov_b32_e32 v0, 0x1400
	v_mov_b32_e32 v1, 1
	global_atomic_add v4, v0, v1, s[6:7] sc0
	s_mov_b32 s13, 0
	s_add_u32 s14, s84, 0x2480
	s_addc_u32 s15, s85, 0
	s_waitcnt lgkmcnt(0)
	v_readfirstlane_b32 s10, v2
	v_readfirstlane_b32 s11, v3
	v_mov_b32_e32 v0, 0
	s_nop 3
	s_mul_i32 s10, s10, 23
	s_mul_i32 s11, s11, 22
	s_waitcnt vmcnt(0)
	v_readfirstlane_b32 s12, v4
	s_nop 3
	s_add_u32 s12, s12, 1
	s_cmp_lg_u32 s12, s10
	s_cbranch_scc1 .Lgb28_poll
	buffer_wbl2 sc1
	s_waitcnt vmcnt(0)
	global_atomic_add v0, v1, s[14:15] offset:0
	global_atomic_add v0, v1, s[14:15] offset:256
	global_atomic_add v0, v1, s[14:15] offset:512
	global_atomic_add v0, v1, s[14:15] offset:768
	global_atomic_add v0, v1, s[14:15] offset:1024
	global_atomic_add v0, v1, s[14:15] offset:1280
	global_atomic_add v0, v1, s[14:15] offset:1536
	global_atomic_add v0, v1, s[14:15] offset:1792
	global_atomic_add v0, v1, s[14:15] offset:2048
	global_atomic_add v0, v1, s[14:15] offset:2304
	global_atomic_add v0, v1, s[14:15] offset:2560
	global_atomic_add v0, v1, s[14:15] offset:2816
	global_atomic_add v0, v1, s[14:15] offset:3072
	global_atomic_add v0, v1, s[14:15] offset:3328
	global_atomic_add v0, v1, s[14:15] offset:3584
	global_atomic_add v0, v1, s[14:15] offset:3840
	v_mov_b32_e32 v0, 0x2480

.Lr29_end:
.LBB0_2733:
	s_cmp_lt_i32 s61, 30
	s_cbranch_scc1 .LBB0_2787
	s_waitcnt vmcnt(0)
	s_barrier
	v_readfirstlane_b32 s2, v162
	s_and_b32 s3, s58, 7
	s_lshl_b32 s3, s3, 8
	s_bfe_u32 s6, s58, 0x30003
	s_lshl_b32 s6, s6, 2
	s_add_u32 s3, s3, s6
	s_add_u32 s3, s3, 0x38c0
	s_add_u32 s6, s84, s3
	s_addc_u32 s7, s85, 0
	s_cmp_lg_u32 s2, 0
	s_cbranch_scc1 .Lgs29_wait
	s_mov_b64 s[8:9], exec
	s_mov_b64 exec, 1
	v_mov_b32_e32 v0, 0
	v_mov_b32_e32 v1, 1
	s_mov_b32 s10, 0
	global_atomic_add v0, v1, s[6:7]
	s_sleep 40

.LBB0_2791:
	s_or_b64 exec, exec, s[10:11]
	s_cmp_lt_u32 s61, 31
	s_cbranch_scc1 .LBB0_2845
	s_waitcnt vmcnt(0) lgkmcnt(0)
	s_barrier
	v_readfirstlane_b32 s2, v162
	s_lshl_b32 s3, s33, 8
	s_add_u32 s6, s84, s3
	s_addc_u32 s7, s85, 0
	s_cmp_lg_u32 s2, 0
	s_cbranch_scc1 .Lgb30_wait
	s_mov_b64 s[8:9], exec
	s_mov_b64 exec, 1
	v_mov_b32_e32 v0, 0x12000
	ds_read_b64 v[2:3], v0
	v_mov_b32_e32 v0, 0x1400
	v_mov_b32_e32 v1, 1
	global_atomic_add v4, v0, v1, s[6:7] sc0
	s_mov_b32 s13, 0
	s_add_u32 s14, s84, 0x2480
	s_addc_u32 s15, s85, 0
	s_waitcnt lgkmcnt(0)
	v_readfirstlane_b32 s10, v2
	v_readfirstlane_b32 s11, v3
	v_mov_b32_e32 v0, 0
	s_nop 3
	s_mul_i32 s10, s10, 24
	s_mul_i32 s11, s11, 23
	s_waitcnt vmcnt(0)
	v_readfirstlane_b32 s12, v4
	s_nop 3
	s_add_u32 s12, s12, 1
	s_cmp_lg_u32 s12, s10
	s_cbranch_scc1 .Lgb30_poll
	buffer_wbl2 sc1
	s_waitcnt vmcnt(0)
	global_atomic_add v0, v1, s[14:15] offset:0
	global_atomic_add v0, v1, s[14:15] offset:256
	global_atomic_add v0, v1, s[14:15] offset:512
	global_atomic_add v0, v1, s[14:15] offset:768
	global_atomic_add v0, v1, s[14:15] offset:1024
	global_atomic_add v0, v1, s[14:15] offset:1280
	global_atomic_add v0, v1, s[14:15] offset:1536
	global_atomic_add v0, v1, s[14:15] offset:1792
	global_atomic_add v0, v1, s[14:15] offset:2048
	global_atomic_add v0, v1, s[14:15] offset:2304
	global_atomic_add v0, v1, s[14:15] offset:2560
	global_atomic_add v0, v1, s[14:15] offset:2816
	global_atomic_add v0, v1, s[14:15] offset:3072
	global_atomic_add v0, v1, s[14:15] offset:3328
	global_atomic_add v0, v1, s[14:15] offset:3584
	global_atomic_add v0, v1, s[14:15] offset:3840
	v_mov_b32_e32 v0, 0x2480

.Lf31_end:
.LBB0_2855:
	s_cmp_lt_i32 s61, 32
	s_cbranch_scc1 .LBB0_2909
	s_waitcnt vmcnt(0) lgkmcnt(0)
	s_barrier
	v_readfirstlane_b32 s2, v162
	s_lshl_b32 s3, s33, 8
	s_add_u32 s6, s84, s3
	s_addc_u32 s7, s85, 0
	s_cmp_lg_u32 s2, 0
	s_cbranch_scc1 .Lgb31_wait
	s_mov_b64 s[8:9], exec
	s_mov_b64 exec, 1
	v_mov_b32_e32 v0, 0x12000
	ds_read_b64 v[2:3], v0
	v_mov_b32_e32 v0, 0x1400
	v_mov_b32_e32 v1, 1
	global_atomic_add v4, v0, v1, s[6:7] sc0
	s_mov_b32 s13, 0
	s_add_u32 s14, s84, 0x2480
	s_addc_u32 s15, s85, 0
	s_waitcnt lgkmcnt(0)
	v_readfirstlane_b32 s10, v2
	v_readfirstlane_b32 s11, v3
	v_mov_b32_e32 v0, 0
	s_nop 3
	s_mul_i32 s10, s10, 25
	s_mul_i32 s11, s11, 24
	s_waitcnt vmcnt(0)
	v_readfirstlane_b32 s12, v4
	s_nop 3
	s_add_u32 s12, s12, 1
	s_cmp_lg_u32 s12, s10
	s_cbranch_scc1 .Lgb31_poll
	buffer_wbl2 sc1
	s_waitcnt vmcnt(0)
	global_atomic_add v0, v1, s[14:15] offset:0
	global_atomic_add v0, v1, s[14:15] offset:256
	global_atomic_add v0, v1, s[14:15] offset:512
	global_atomic_add v0, v1, s[14:15] offset:768
	global_atomic_add v0, v1, s[14:15] offset:1024
	global_atomic_add v0, v1, s[14:15] offset:1280
	global_atomic_add v0, v1, s[14:15] offset:1536
	global_atomic_add v0, v1, s[14:15] offset:1792
	global_atomic_add v0, v1, s[14:15] offset:2048
	global_atomic_add v0, v1, s[14:15] offset:2304
	global_atomic_add v0, v1, s[14:15] offset:2560
	global_atomic_add v0, v1, s[14:15] offset:2816
	global_atomic_add v0, v1, s[14:15] offset:3072
	global_atomic_add v0, v1, s[14:15] offset:3328
	global_atomic_add v0, v1, s[14:15] offset:3584
	global_atomic_add v0, v1, s[14:15] offset:3840
	v_mov_b32_e32 v0, 0x2480

.Lr32_end:
.LBB0_2915:
	s_cmp_lt_i32 s61, 33
	s_cbranch_scc1 .LBB0_2969
	s_waitcnt vmcnt(0)
	s_barrier
	v_readfirstlane_b32 s2, v162
	s_and_b32 s3, s58, 7
	s_lshl_b32 s3, s3, 8
	s_bfe_u32 s6, s58, 0x30003
	s_lshl_b32 s6, s6, 2
	s_add_u32 s3, s3, s6
	s_add_u32 s3, s3, 0x38e0
	s_add_u32 s6, s84, s3
	s_addc_u32 s7, s85, 0
	s_cmp_lg_u32 s2, 0
	s_cbranch_scc1 .Lgs32_wait
	s_mov_b64 s[8:9], exec
	s_mov_b64 exec, 1
	v_mov_b32_e32 v0, 0
	v_mov_b32_e32 v1, 1
	s_mov_b32 s10, 0
	global_atomic_add v0, v1, s[6:7]
	s_sleep 40
